# static s_setprio 1 for waves 0-3 during the four attention phases, on top of aligned GEMM K-loops + MMA-path cleanup
# speedup vs baseline: 1.0034x; 1.0034x over previous
.LBB0_439:
	v_readfirstlane_b32 s99, v0
	s_lshr_b32 s99, s99, 6
	s_cmp_lt_u32 s99, 4
	s_cbranch_scc0 .Lmy_pr_3
	s_setprio 1

.LBB0_729:
	s_setprio 0
	s_cmp_lt_i32 s28, 5
	s_cselect_b64 s[4:5], -1, 0
	s_cmp_gt_i32 s29, 4
	s_cselect_b64 s[6:7], -1, 0
	s_and_b64 s[4:5], s[4:5], s[6:7]
	s_andn2_b64 vcc, exec, s[4:5]
	s_cbranch_vccnz .LBB0_832
	s_mov_b32 s3, 0
	s_mov_b64 s[8:9], s[22:23]
	s_mul_hi_i32 s4, s3, 0xb800000
	s_mul_i32 s3, s3, 0xb800000
	s_add_u32 s26, s8, s3
	s_addc_u32 s27, s9, s4
	s_add_u32 s6, s8, 0x2b200000
	s_addc_u32 s7, s9, 0
	s_mov_b32 s3, s80
	s_mov_b32 s18, s2
	s_waitcnt vmcnt(0)
	v_mov_b32_e32 v10, v0
	s_cmpk_gt_i32 s18, 0x3ff
	v_readfirstlane_b32 s14, v10
	s_cbranch_scc1 .LBB0_754
	s_ashr_i32 s19, s18, 31
	s_lshr_b32 s4, s19, 29
	s_add_i32 s12, s18, s4
	s_and_b32 s4, s12, -8
	s_sub_i32 s11, s18, s4
	s_cmp_gt_i32 s11, -1
	s_cbranch_scc0 .LBB0_733
	s_lshl_b32 s10, s11, 7
	s_ashr_i32 s4, s12, 3
	s_cbranch_execz .LBB0_734
	s_branch .LBB0_735

.LBB0_1024:
	s_setprio 0
	s_cmp_lt_i32 s28, 9
	s_cselect_b64 s[4:5], -1, 0
	s_cmp_gt_i32 s29, 8
	s_cselect_b64 s[6:7], -1, 0
	s_and_b64 s[4:5], s[4:5], s[6:7]
	s_andn2_b64 vcc, exec, s[4:5]
	s_cbranch_vccnz .LBB0_1095
	s_mov_b32 s6, 0
	s_mov_b64 s[4:5], s[22:23]
	s_mov_b32 s3, s80
	s_mov_b32 s18, s2
	s_waitcnt vmcnt(0)
	v_mov_b32_e32 v10, v0
	s_cmpk_gt_i32 s18, 0x3ff
	v_readfirstlane_b32 s9, v10
	s_cbranch_scc1 .LBB0_1041
	v_lshlrev_b32_e32 v1, 4, v10
	v_add_u32_e32 v2, 0x2000, v1
	v_ashrrev_i32_e32 v3, 31, v2
	v_lshrrev_b32_e32 v3, 22, v3
	v_add_u32_e32 v3, v2, v3
	v_ashrrev_i32_e32 v11, 10, v3
	v_mul_i32_i24_e32 v3, 0x400, v11
	v_sub_u32_e32 v2, v2, v3
	v_lshrrev_b32_e32 v3, 4, v2
	v_bitop3_b32 v2, v3, v2, 32 bitop3:0x6c
	s_mul_hi_i32 s7, s6, 0xb800000
	s_mul_i32 s6, s6, 0xb800000
	v_ashrrev_i32_e32 v3, 31, v2
	s_add_u32 s6, s4, s6
	v_lshrrev_b32_e32 v3, 26, v3
	s_addc_u32 s7, s5, s7
	v_add_u32_e32 v3, v2, v3
	v_lshlrev_b32_e32 v4, 3, v11
	s_add_u32 s19, s4, 0x27200000
	v_ashrrev_i32_e32 v12, 6, v3
	v_and_b32_e32 v4, -16, v4
	s_addc_u32 s24, s5, 0
	v_add_u32_e32 v4, v12, v4
	s_add_u32 s25, s6, 0xb200000
	v_and_b32_e32 v5, 3, v12
	s_mov_b32 s6, 0x3fffe0
	v_lshrrev_b32_e32 v6, 2, v4
	v_lshlrev_b32_e32 v7, 1, v4
	v_and_b32_e32 v3, 0xc0, v3
	v_and_or_b32 v5, v4, s6, v5
	v_and_b32_e32 v6, 4, v6
	v_and_b32_e32 v7, 24, v7
	v_sub_u32_e32 v2, v2, v3
	v_mov_b32_e32 v3, 1
	v_or3_b32 v5, v5, v6, v7
	v_lshlrev_b32_e32 v6, 5, v11
	v_ashrrev_i16_sdwa v2, v3, sext(v2) dst_sel:DWORD dst_unused:UNUSED_PAD src0_sel:DWORD src1_sel:BYTE_0
	v_and_b32_e32 v6, 32, v6
	v_bfe_i32 v13, v2, 0, 16
	v_add_lshl_u32 v2, v6, v13, 1
	v_lshl_add_u32 v162, v5, 10, v2
	v_lshl_add_u32 v164, v4, 10, v2
	v_bfe_i32 v2, v10, 27, 1
	v_lshrrev_b32_e32 v2, 22, v2
	v_add_u32_e32 v2, v1, v2
	v_and_b32_e32 v2, 0xfffffc00, v2
	v_sub_u32_e32 v1, v1, v2
	v_lshrrev_b32_e32 v2, 4, v1
	v_ashrrev_i32_e32 v4, 31, v10
	v_bitop3_b32 v1, v2, v1, 32 bitop3:0x6c
	v_lshrrev_b32_e32 v4, 26, v4
	v_ashrrev_i32_e32 v2, 31, v1
	v_add_u32_e32 v4, v10, v4
	v_lshrrev_b32_e32 v2, 26, v2
	v_ashrrev_i32_e32 v15, 6, v4
	v_add_u32_e32 v2, v1, v2
	v_lshlrev_b32_e32 v4, 3, v15
	v_ashrrev_i32_e32 v14, 6, v2
	v_and_b32_e32 v4, -16, v4
	s_addc_u32 s26, s7, 0
	v_add_u32_e32 v4, v14, v4
	v_and_b32_e32 v5, 3, v14
	s_ashr_i32 s37, s18, 31
	v_and_or_b32 v5, v4, s6, v5
	s_lshr_b32 s6, s37, 29
	s_add_i32 s6, s18, s6
	s_ashr_i32 s11, s9, 6
	s_ashr_i32 s7, s6, 3
	s_and_b32 s6, s6, -8
	s_ashr_i32 s10, s9, 8
	s_lshl_b32 s27, s11, 10
	s_sub_i32 s6, s18, s6
	s_cmp_lt_i32 s6, 0
	s_movk_i32 s60, 0x81
	s_cselect_b32 s8, s60, 0x80
	s_mul_i32 s6, s8, s6
	s_add_i32 s6, s6, s7
	s_ashr_i32 s7, s6, 31
	s_lshr_b32 s7, s7, 25
	s_add_i32 s7, s6, s7
	v_lshrrev_b32_e32 v6, 2, v4
	v_lshlrev_b32_e32 v7, 1, v4
	v_and_b32_e32 v2, 0xc0, v2
	s_ashr_i32 s8, s7, 7
	v_and_b32_e32 v6, 4, v6
	v_and_b32_e32 v7, 24, v7
	v_sub_u32_e32 v1, v1, v2
	s_lshl_b32 s12, s8, 3
	v_or3_b32 v5, v5, v6, v7
	v_lshlrev_b32_e32 v6, 5, v15
	v_ashrrev_i16_sdwa v1, v3, sext(v1) dst_sel:DWORD dst_unused:UNUSED_PAD src0_sel:DWORD src1_sel:BYTE_0
	s_sub_i32 s8, 64, s12
	v_and_b32_e32 v6, 32, v6
	v_bfe_i32 v16, v1, 0, 16
	s_min_u32 s13, s8, 8
	s_and_b32 s7, s7, 0xffffff80
	v_add_lshl_u32 v1, v6, v16, 1
	s_sub_i32 s14, s6, s7
	v_cvt_f32_ubyte0_e32 v3, s13
	v_lshl_add_u32 v166, v5, 10, v1
	v_cvt_f32_i32_e32 v2, s14
	v_rcp_iflag_f32_e32 v5, v3
	v_lshl_add_u32 v168, v4, 10, v1
	s_ashr_i32 s6, s14, 30
	s_or_b32 s8, s6, 1
	v_mul_f32_e32 v1, v2, v5
	v_trunc_f32_e32 v1, v1
	v_fma_f32 v2, -v1, v3, v2
	v_cvt_i32_f32_e32 v1, v1
	v_cmp_ge_f32_e64 s[6:7], |v2|, v3
	s_and_b64 s[6:7], s[6:7], exec
	s_cselect_b32 s6, s8, 0
	v_readfirstlane_b32 s7, v1
	s_add_i32 s8, s7, s6
	s_mul_i32 s6, s8, s13
	s_sub_i32 s6, s14, s6
	s_sext_i32_i8 s6, s6
	s_add_i32 s54, s12, s6
	s_ashr_i32 s55, s54, 31
	s_bfe_i64 s[12:13], s[8:9], 0x80000
	s_lshl_b64 s[6:7], s[54:55], 18
	s_lshl_b64 s[12:13], s[12:13], 18
	s_add_u32 s56, s25, s12
	s_addc_u32 s57, s26, s13
	s_add_i32 s55, s27, 0
	s_add_i32 m0, s55, 0x10000
	v_mov_b32_e32 v167, 0
	global_load_lds_dwordx4 v166, s[56:57]
	s_add_i32 m0, s55, 0x12000
	s_add_u32 s12, s56, 0x20000
	global_load_lds_dwordx4 v162, s[56:57]
	s_addc_u32 s13, s57, 0
	s_add_i32 m0, s55, 0x14000
	v_mov_b32_e32 v163, v167
	global_load_lds_dwordx4 v166, s[12:13]
	s_add_i32 m0, s55, 0x16000
	s_add_u32 s58, s19, s6
	s_addc_u32 s59, s24, s7
	s_add_i32 s61, s55, 0x2000
	global_load_lds_dwordx4 v162, s[12:13]
	s_mov_b32 m0, s55
	s_add_u32 s6, s58, 0x20000
	global_load_lds_dwordx4 v168, s[58:59]
	s_mov_b32 m0, s61
	s_addc_u32 s7, s59, 0
	s_add_i32 s62, s55, 0x4000
	global_load_lds_dwordx4 v164, s[58:59]
	s_mov_b32 m0, s62
	s_add_i32 s63, s55, 0x6000
	global_load_lds_dwordx4 v168, s[6:7]
	s_mov_b32 m0, s63
	v_mov_b32_e32 v169, v167
	global_load_lds_dwordx4 v164, s[6:7]
	v_mov_b32_e32 v165, v167
	s_cmp_eq_u32 s10, 1
	v_lshl_add_u64 v[8:9], s[56:57], 0, v[166:167]
	v_lshl_add_u64 v[6:7], s[56:57], 0, v[162:163]
	v_lshl_add_u64 v[2:3], s[58:59], 0, v[168:169]
	s_cselect_b64 s[6:7], -1, 0
	s_cmp_lg_u32 s10, 1
	v_lshl_add_u64 v[4:5], s[58:59], 0, v[164:165]
	s_cbranch_scc1 .LBB0_1028
	s_barrier

.LBB0_1310:
	s_setprio 0
	s_cmp_lt_i32 s28, 14
	s_cselect_b64 s[4:5], -1, 0
	s_cmp_gt_i32 s29, 13
	s_cselect_b64 s[6:7], -1, 0
	s_and_b64 s[4:5], s[4:5], s[6:7]
	s_andn2_b64 vcc, exec, s[4:5]
	s_mov_b32 s9, 1
	s_cbranch_vccnz .LBB0_1389
	s_mov_b64 s[4:5], s[22:23]
	s_mov_b32 s3, s2
	s_mov_b32 s18, s80
	s_waitcnt vmcnt(0)
	v_mov_b32_e32 v10, v0
	s_cmpk_gt_i32 s3, 0x3ff
	v_readfirstlane_b32 s15, v10
	s_cbranch_scc1 .LBB0_1335
	s_ashr_i32 s19, s3, 31
	s_lshr_b32 s6, s19, 29
	s_add_i32 s11, s3, s6
	s_and_b32 s6, s11, -8
	s_sub_i32 s10, s3, s6
	s_cmp_gt_i32 s10, -1
	s_cbranch_scc0 .LBB0_1314
	s_lshl_b32 s8, s10, 7
	s_ashr_i32 s6, s11, 3
	s_cbranch_execz .LBB0_1315
	s_branch .LBB0_1316

.LBB0_1581:
	s_setprio 0
	s_cmp_lt_i32 s28, 18
	s_cselect_b64 s[4:5], -1, 0
	s_cmp_gt_i32 s29, 17
	s_cselect_b64 s[6:7], -1, 0
	s_and_b64 s[4:5], s[4:5], s[6:7]
	s_andn2_b64 vcc, exec, s[4:5]
	s_mov_b32 s6, 1
	s_cbranch_vccnz .LBB0_1652
	s_mov_b64 s[4:5], s[22:23]
	s_mov_b32 s3, s80
	s_waitcnt vmcnt(0)
	v_mov_b32_e32 v10, v0
	s_cmpk_gt_i32 s2, 0x3ff
	v_readfirstlane_b32 s9, v10
	s_cbranch_scc1 .LBB0_1598
	v_lshlrev_b32_e32 v1, 4, v10
	v_add_u32_e32 v2, 0x2000, v1
	v_ashrrev_i32_e32 v3, 31, v2
	v_lshrrev_b32_e32 v3, 22, v3
	v_add_u32_e32 v3, v2, v3
	v_ashrrev_i32_e32 v11, 10, v3
	v_mul_i32_i24_e32 v3, 0x400, v11
	v_sub_u32_e32 v2, v2, v3
	v_lshrrev_b32_e32 v3, 4, v2
	v_bitop3_b32 v2, v3, v2, 32 bitop3:0x6c
	s_mul_hi_i32 s7, s6, 0xb800000
	s_mul_i32 s6, s6, 0xb800000
	v_ashrrev_i32_e32 v3, 31, v2
	s_add_u32 s6, s4, s6
	v_lshrrev_b32_e32 v3, 26, v3
	s_addc_u32 s7, s5, s7
	v_add_u32_e32 v3, v2, v3
	v_lshlrev_b32_e32 v4, 3, v11
	s_add_u32 s18, s4, 0x27200000
	v_ashrrev_i32_e32 v12, 6, v3
	v_and_b32_e32 v4, -16, v4
	s_addc_u32 s19, s5, 0
	v_add_u32_e32 v4, v12, v4
	s_add_u32 s24, s6, 0xb200000
	v_and_b32_e32 v5, 3, v12
	s_mov_b32 s6, 0x3fffe0
	v_lshrrev_b32_e32 v6, 2, v4
	v_lshlrev_b32_e32 v7, 1, v4
	v_and_b32_e32 v3, 0xc0, v3
	v_and_or_b32 v5, v4, s6, v5
	v_and_b32_e32 v6, 4, v6
	v_and_b32_e32 v7, 24, v7
	v_sub_u32_e32 v2, v2, v3
	v_mov_b32_e32 v3, 1
	v_or3_b32 v5, v5, v6, v7
	v_lshlrev_b32_e32 v6, 5, v11
	v_ashrrev_i16_sdwa v2, v3, sext(v2) dst_sel:DWORD dst_unused:UNUSED_PAD src0_sel:DWORD src1_sel:BYTE_0
	v_and_b32_e32 v6, 32, v6
	v_bfe_i32 v13, v2, 0, 16
	v_add_lshl_u32 v2, v6, v13, 1
	v_lshl_add_u32 v162, v5, 10, v2
	v_lshl_add_u32 v164, v4, 10, v2
	v_bfe_i32 v2, v10, 27, 1
	v_lshrrev_b32_e32 v2, 22, v2
	v_add_u32_e32 v2, v1, v2
	v_and_b32_e32 v2, 0xfffffc00, v2
	v_sub_u32_e32 v1, v1, v2
	v_lshrrev_b32_e32 v2, 4, v1
	v_ashrrev_i32_e32 v4, 31, v10
	v_bitop3_b32 v1, v2, v1, 32 bitop3:0x6c
	v_lshrrev_b32_e32 v4, 26, v4
	v_ashrrev_i32_e32 v2, 31, v1
	v_add_u32_e32 v4, v10, v4
	v_lshrrev_b32_e32 v2, 26, v2
	v_ashrrev_i32_e32 v15, 6, v4
	v_add_u32_e32 v2, v1, v2
	v_lshlrev_b32_e32 v4, 3, v15
	v_ashrrev_i32_e32 v14, 6, v2
	v_and_b32_e32 v4, -16, v4
	s_addc_u32 s25, s7, 0
	v_add_u32_e32 v4, v14, v4
	v_and_b32_e32 v5, 3, v14
	s_ashr_i32 s27, s2, 31
	v_and_or_b32 v5, v4, s6, v5
	s_lshr_b32 s6, s27, 29
	s_add_i32 s6, s2, s6
	s_ashr_i32 s11, s9, 6
	s_ashr_i32 s7, s6, 3
	s_and_b32 s6, s6, -8
	s_ashr_i32 s10, s9, 8
	s_lshl_b32 s26, s11, 10
	s_sub_i32 s6, s2, s6
	s_cmp_lt_i32 s6, 0
	s_movk_i32 s37, 0x81
	s_cselect_b32 s8, s37, 0x80
	s_mul_i32 s6, s8, s6
	s_add_i32 s6, s6, s7
	s_ashr_i32 s7, s6, 31
	s_lshr_b32 s7, s7, 25
	s_add_i32 s7, s6, s7
	v_lshrrev_b32_e32 v6, 2, v4
	v_lshlrev_b32_e32 v7, 1, v4
	v_and_b32_e32 v2, 0xc0, v2
	s_ashr_i32 s8, s7, 7
	v_and_b32_e32 v6, 4, v6
	v_and_b32_e32 v7, 24, v7
	v_sub_u32_e32 v1, v1, v2
	s_lshl_b32 s12, s8, 3
	v_or3_b32 v5, v5, v6, v7
	v_lshlrev_b32_e32 v6, 5, v15
	v_ashrrev_i16_sdwa v1, v3, sext(v1) dst_sel:DWORD dst_unused:UNUSED_PAD src0_sel:DWORD src1_sel:BYTE_0
	s_sub_i32 s8, 64, s12
	v_and_b32_e32 v6, 32, v6
	v_bfe_i32 v16, v1, 0, 16
	s_min_u32 s13, s8, 8
	s_and_b32 s7, s7, 0xffffff80
	v_add_lshl_u32 v1, v6, v16, 1
	s_sub_i32 s14, s6, s7
	v_cvt_f32_ubyte0_e32 v3, s13
	v_lshl_add_u32 v166, v5, 10, v1
	v_cvt_f32_i32_e32 v2, s14
	v_rcp_iflag_f32_e32 v5, v3
	v_lshl_add_u32 v168, v4, 10, v1
	s_ashr_i32 s6, s14, 30
	s_or_b32 s8, s6, 1
	v_mul_f32_e32 v1, v2, v5
	v_trunc_f32_e32 v1, v1
	v_fma_f32 v2, -v1, v3, v2
	v_cvt_i32_f32_e32 v1, v1
	v_cmp_ge_f32_e64 s[6:7], |v2|, v3
	s_and_b64 s[6:7], s[6:7], exec
	s_cselect_b32 s6, s8, 0
	v_readfirstlane_b32 s7, v1
	s_add_i32 s8, s7, s6
	s_mul_i32 s6, s8, s13
	s_sub_i32 s6, s14, s6
	s_sext_i32_i8 s6, s6
	s_add_i32 s54, s12, s6
	s_ashr_i32 s55, s54, 31
	s_bfe_i64 s[12:13], s[8:9], 0x80000
	s_lshl_b64 s[6:7], s[54:55], 18
	s_lshl_b64 s[12:13], s[12:13], 18
	s_add_u32 s56, s24, s12
	s_addc_u32 s57, s25, s13
	s_add_i32 s55, s26, 0
	s_add_i32 m0, s55, 0x10000
	v_mov_b32_e32 v167, 0
	global_load_lds_dwordx4 v166, s[56:57]
	s_add_i32 m0, s55, 0x12000
	s_add_u32 s12, s56, 0x20000
	global_load_lds_dwordx4 v162, s[56:57]
	s_addc_u32 s13, s57, 0
	s_add_i32 m0, s55, 0x14000
	v_mov_b32_e32 v163, v167
	global_load_lds_dwordx4 v166, s[12:13]
	s_add_i32 m0, s55, 0x16000
	s_add_u32 s58, s18, s6
	s_addc_u32 s59, s19, s7
	s_add_i32 s60, s55, 0x2000
	global_load_lds_dwordx4 v162, s[12:13]
	s_mov_b32 m0, s55
	s_add_u32 s6, s58, 0x20000
	global_load_lds_dwordx4 v168, s[58:59]
	s_mov_b32 m0, s60
	s_addc_u32 s7, s59, 0
	s_add_i32 s61, s55, 0x4000
	global_load_lds_dwordx4 v164, s[58:59]
	s_mov_b32 m0, s61
	s_add_i32 s62, s55, 0x6000
	global_load_lds_dwordx4 v168, s[6:7]
	s_mov_b32 m0, s62
	v_mov_b32_e32 v169, v167
	global_load_lds_dwordx4 v164, s[6:7]
	v_mov_b32_e32 v165, v167
	s_cmp_eq_u32 s10, 1
	s_mov_b32 s63, 0
	v_lshl_add_u64 v[8:9], s[56:57], 0, v[166:167]
	v_lshl_add_u64 v[6:7], s[56:57], 0, v[162:163]
	v_lshl_add_u64 v[2:3], s[58:59], 0, v[168:169]
	s_cselect_b64 s[6:7], -1, 0
	s_cmp_lg_u32 s10, 1
	v_lshl_add_u64 v[4:5], s[58:59], 0, v[164:165]
	s_cbranch_scc1 .LBB0_1585
	s_barrier

	.amdhsa_kernel _Z8mega_fwd4Args
		.amdhsa_group_segment_fixed_size 0
		.amdhsa_private_segment_fixed_size 0
		.amdhsa_kernarg_size 456
		.amdhsa_user_sgpr_count 2
		.amdhsa_user_sgpr_dispatch_ptr 0
		.amdhsa_user_sgpr_queue_ptr 0
		.amdhsa_user_sgpr_kernarg_segment_ptr 1
		.amdhsa_user_sgpr_dispatch_id 0
		.amdhsa_user_sgpr_kernarg_preload_length 0
		.amdhsa_user_sgpr_kernarg_preload_offset 0
		.amdhsa_user_sgpr_private_segment_size 0
		.amdhsa_uses_dynamic_stack 0
		.amdhsa_enable_private_segment 0
		.amdhsa_system_sgpr_workgroup_id_x 1
		.amdhsa_system_sgpr_workgroup_id_y 0
		.amdhsa_system_sgpr_workgroup_id_z 0
		.amdhsa_system_sgpr_workgroup_info 0
		.amdhsa_system_vgpr_workitem_id 0
		.amdhsa_next_free_vgpr 256
		.amdhsa_next_free_sgpr 102
		.amdhsa_accum_offset 256
		.amdhsa_reserve_vcc 1
		.amdhsa_float_round_mode_32 0
		.amdhsa_float_round_mode_16_64 0
		.amdhsa_float_denorm_mode_32 3
		.amdhsa_float_denorm_mode_16_64 3
		.amdhsa_dx10_clamp 1
		.amdhsa_ieee_mode 1
		.amdhsa_fp16_overflow 0
		.amdhsa_tg_split 0
		.amdhsa_exception_fp_ieee_invalid_op 0
		.amdhsa_exception_fp_denorm_src 0
		.amdhsa_exception_fp_ieee_div_zero 0
		.amdhsa_exception_fp_ieee_overflow 0
		.amdhsa_exception_fp_ieee_underflow 0
		.amdhsa_exception_fp_ieee_inexact 0
		.amdhsa_exception_int_div_zero 0
	.end_amdhsa_kernel

amdhsa.kernels:
  - .agpr_count:     0
    .args:
      - .offset:         0
        .size:           200
        .value_kind:     by_value
      - .offset:         200
        .size:           4
        .value_kind:     hidden_block_count_x
      - .offset:         204
        .size:           4
        .value_kind:     hidden_block_count_y
      - .offset:         208
        .size:           4
        .value_kind:     hidden_block_count_z
      - .offset:         212
        .size:           2
        .value_kind:     hidden_group_size_x
      - .offset:         214
        .size:           2
        .value_kind:     hidden_group_size_y
      - .offset:         216
        .size:           2
        .value_kind:     hidden_group_size_z
      - .offset:         218
        .size:           2
        .value_kind:     hidden_remainder_x
      - .offset:         220
        .size:           2
        .value_kind:     hidden_remainder_y
      - .offset:         222
        .size:           2
        .value_kind:     hidden_remainder_z
      - .offset:         240
        .size:           8
        .value_kind:     hidden_global_offset_x
      - .offset:         248
        .size:           8
        .value_kind:     hidden_global_offset_y
      - .offset:         256
        .size:           8
        .value_kind:     hidden_global_offset_z
      - .offset:         264
        .size:           2
        .value_kind:     hidden_grid_dims
      - .offset:         320
        .size:           4
        .value_kind:     hidden_dynamic_lds_size
    .group_segment_fixed_size: 0
    .kernarg_segment_align: 8
    .kernarg_segment_size: 456
    .language:       OpenCL C
    .language_version:
      - 2
      - 0
    .max_flat_workgroup_size: 512
    .name:           _Z8mega_fwd4Args
    .private_segment_fixed_size: 0
    .sgpr_count:     108
    .sgpr_spill_count: 14
    .symbol:         _Z8mega_fwd4Args.kd
    .uniform_work_group_size: 1
    .uses_dynamic_stack: false
    .vgpr_count:     256
    .vgpr_spill_count: 0
    .wavefront_size: 64
